# in-loop pre-norm phase rewritten: scalar row control, hoisted g/(1+sc)/sh, x rows double-buffered with counted vmcnt
# speedup vs baseline: 1.0092x; 1.0034x over previous
; __device__ __forceinline__ void phase_prep(const Params& p, int l, int mode) {
;     asm volatile("" : "+s"(l), "+s"(mode));
;     int tid = threadIdx.x; asm volatile("" : "+v"(tid));
;     const int lane = tid & 63, w = tid >> 6;
;     const float* g = p.norm_g + l * D;
;     const int xb_ = blockIdx.x & 7, xj_ = (int)(blockIdx.x >> 3) - (mode == 1 ? 4 : 0), xn_ = (int)(gridDim.x >> 3) - (mode == 1 ? 4 : 0);
;     const int lr_lo = mode == 2 ? SEQ : 0, lr_hi = mode == 1 ? SEQ : SEQ + CTXL;
;     for (int lrow = lr_lo + xj_ * 8 + w; lrow < lr_hi; lrow += xn_ * 8) {
;         const int row = lrow < SEQ ? xb_ * SEQ + lrow : MLAT + xb_ * CTXL + (lrow - SEQ);
;         const float* xr = xin_row(p, l, row);
;         const int bv = row < MLAT ? (row >> 12) : 8;
;         const float* md = p.mod + ((size_t)l * 9 + bv) * 3072;
;         float4 v[4]; float ss = 0.f;
; #pragma unroll
;         for (int j = 0; j < 4; ++j) {
;             v[j] = *(const float4*)(xr + j * 256 + lane * 4);
;             ss += v[j].x * v[j].x + v[j].y * v[j].y + v[j].z * v[j].z + v[j].w * v[j].w;
;         }
; #pragma unroll
;         for (int o = 32; o >= 1; o >>= 1) ss += __shfl_xor(ss, o);
;         const float rstd = rsqrtf(ss * (1.0f / 1024.0f) + EPS);
.LBB0_772:
	s_cmp_eq_u32 s40, 2
	s_cselect_b32 s10, 0x1000, 0
	s_cmp_eq_u32 s40, 1
	s_cselect_b32 s5, 0xffffffe0, 0
	s_cselect_b32 s13, s82, 0x1100
	s_add_i32 s11, s5, s94
	s_and_b32 s11, s11, -8
	s_add_i32 s11, s11, s10
	v_readfirstlane_b32 s4, v234
	s_add_i32 s5, s5, s92
	s_and_b32 s12, s5, -8
	s_nop 1
	s_lshr_b32 s4, s4, 6
	s_add_i32 s14, s11, s4
	s_cmp_ge_i32 s14, s13
	s_cbranch_scc1 .Lprep2_exit
	s_and_b32 s5, s94, 7
	v_readlane_b32 s16, v253, 42
	v_readlane_b32 s17, v253, 43
	v_readlane_b32 s18, v253, 44
	v_readlane_b32 s19, v253, 45
	v_readlane_b32 s20, v253, 46
	v_readlane_b32 s21, v253, 47
	v_readlane_b32 s22, v253, 10
	v_readlane_b32 s23, v253, 11
	v_readlane_b32 s24, v253, 56
	v_readlane_b32 s25, v253, 57
	v_and_b32_e32 v0, 63, v234
	v_lshlrev_b32_e32 v2, 3, v0
	v_lshlrev_b32_e32 v0, 4, v0
	v_xor_b32_e32 v3, 32, v239
	v_lshlrev_b32_e32 v40, 2, v3
	v_xor_b32_e32 v3, 16, v239
	v_lshlrev_b32_e32 v41, 2, v3
	v_xor_b32_e32 v3, 8, v239
	v_lshlrev_b32_e32 v42, 2, v3
	v_xor_b32_e32 v3, 4, v239
	v_lshlrev_b32_e32 v43, 2, v3
	v_xor_b32_e32 v3, 2, v239
	v_lshlrev_b32_e32 v44, 2, v3
	v_xor_b32_e32 v3, 1, v239
	v_lshlrev_b32_e32 v45, 2, v3
	s_cmpk_lt_i32 s14, 0x1000
	s_cbranch_scc0 .Lprep2_ctx
	s_lshl_b32 s4, s5, 24
	s_add_u32 s16, s16, s4
	s_addc_u32 s17, s17, 0
	s_lshl_b32 s4, s5, 23
	s_add_u32 s18, s20, s4
	s_addc_u32 s19, s21, 0
	s_mov_b32 s26, s5
	s_branch .Lprep2_common
.Lprep2_ctx:
	s_lshl_b32 s4, s5, 20
	s_add_u32 s16, s18, s4
	s_addc_u32 s17, s19, 0
	s_sub_u32 s16, s16, 0x1000000
	s_subb_u32 s17, s17, 0
	s_lshl_b32 s4, s5, 19
	s_add_i32 s4, s4, 0x3800000
	s_add_u32 s18, s20, s4
	s_addc_u32 s19, s21, 0
	s_mov_b32 s26, 8
.Lprep2_common:
	s_mul_i32 s4, s33, 9
	s_add_i32 s4, s4, s26
	s_mul_i32 s4, s4, 0x3000
	s_add_u32 s22, s22, s4
	s_addc_u32 s23, s23, 0
	s_lshl_b32 s4, s33, 12
	s_add_u32 s24, s24, s4
	s_addc_u32 s25, s25, 0
	s_add_u32 s26, s22, 0x1000
	s_addc_u32 s27, s23, 0
	global_load_dwordx4 v[60:63], v0, s[24:25]
	global_load_dwordx4 v[64:67], v0, s[24:25] offset:1024
	global_load_dwordx4 v[68:71], v0, s[24:25] offset:2048
	global_load_dwordx4 v[72:75], v0, s[24:25] offset:3072
	global_load_dwordx4 v[76:79], v0, s[26:27]
	global_load_dwordx4 v[80:83], v0, s[26:27] offset:1024
	global_load_dwordx4 v[84:87], v0, s[26:27] offset:2048
	global_load_dwordx4 v[88:91], v0, s[26:27] offset:3072
	global_load_dwordx4 v[92:95], v0, s[22:23]
	global_load_dwordx4 v[96:99], v0, s[22:23] offset:1024
	global_load_dwordx4 v[100:103], v0, s[22:23] offset:2048
	global_load_dwordx4 v[104:107], v0, s[22:23] offset:3072
	s_lshl_b32 s38, s14, 12
	s_add_u32 s34, s16, s38
	s_addc_u32 s35, s17, 0
	global_load_dwordx4 v[108:111], v0, s[34:35]
	global_load_dwordx4 v[112:115], v0, s[34:35] offset:1024
	global_load_dwordx4 v[116:119], v0, s[34:35] offset:2048
	global_load_dwordx4 v[120:123], v0, s[34:35] offset:3072
	s_add_i32 s15, s14, s12
	s_cmp_lt_i32 s15, s13
	s_cselect_b32 s39, s15, s14
	s_lshl_b32 s38, s39, 12
	s_add_u32 s34, s16, s38
	s_addc_u32 s35, s17, 0
	global_load_dwordx4 v[124:127], v0, s[34:35]
	global_load_dwordx4 v[128:131], v0, s[34:35] offset:1024
	global_load_dwordx4 v[132:135], v0, s[34:35] offset:2048
	global_load_dwordx4 v[136:139], v0, s[34:35] offset:3072
	s_add_i32 s15, s15, s12
	s_waitcnt vmcnt(8)
	v_add_f32_e32 v76, 1.0, v76
	v_add_f32_e32 v77, 1.0, v77
	v_add_f32_e32 v78, 1.0, v78
	v_add_f32_e32 v79, 1.0, v79
	v_add_f32_e32 v80, 1.0, v80
	v_add_f32_e32 v81, 1.0, v81
	v_add_f32_e32 v82, 1.0, v82
	v_add_f32_e32 v83, 1.0, v83
	v_add_f32_e32 v84, 1.0, v84
	v_add_f32_e32 v85, 1.0, v85
	v_add_f32_e32 v86, 1.0, v86
	v_add_f32_e32 v87, 1.0, v87
	v_add_f32_e32 v88, 1.0, v88
	v_add_f32_e32 v89, 1.0, v89
	v_add_f32_e32 v90, 1.0, v90
	v_add_f32_e32 v91, 1.0, v91
	s_mov_b32 s29, 0x800000
	s_waitcnt vmcnt(4)
	v_mul_f32_e32 v4, v109, v109
	v_fma_f32 v4, v108, v108, v4
	v_fma_f32 v4, v110, v110, v4
	v_fma_f32 v4, v111, v111, v4
	v_mul_f32_e32 v5, v113, v113
	v_fma_f32 v5, v112, v112, v5
	v_fma_f32 v5, v114, v114, v5
	v_fma_f32 v5, v115, v115, v5
	v_mul_f32_e32 v6, v117, v117
	v_fma_f32 v6, v116, v116, v6
	v_fma_f32 v6, v118, v118, v6
	v_fma_f32 v6, v119, v119, v6
	v_mul_f32_e32 v7, v121, v121
	v_fma_f32 v7, v120, v120, v7
	v_fma_f32 v7, v122, v122, v7
	v_fma_f32 v7, v123, v123, v7
	v_add_f32_e32 v8, v4, v5
	v_add_f32_e32 v8, v8, v6
	v_add_f32_e32 v8, v8, v7
	ds_bpermute_b32 v9, v40, v8
	s_waitcnt lgkmcnt(0)
	v_add_f32_e32 v8, v8, v9
	ds_bpermute_b32 v9, v41, v8
	s_waitcnt lgkmcnt(0)
	v_add_f32_e32 v8, v8, v9
	ds_bpermute_b32 v9, v42, v8
	s_waitcnt lgkmcnt(0)
	v_add_f32_e32 v8, v8, v9
	ds_bpermute_b32 v9, v43, v8
	s_waitcnt lgkmcnt(0)
	v_add_f32_e32 v8, v8, v9
	ds_bpermute_b32 v9, v44, v8
	s_waitcnt lgkmcnt(0)
	v_add_f32_e32 v8, v8, v9
	ds_bpermute_b32 v9, v45, v8
	s_waitcnt lgkmcnt(0)
; __device__ __forceinline__ void phase_prep(const Params& p, int l, int mode) {
;     ...
;         float4 v[4]; float ss = 0.f;
; #pragma unroll
;         for (int j = 0; j < 4; ++j) {
;             v[j] = *(const float4*)(xr + j * 256 + lane * 4);
;             ss += v[j].x * v[j].x + v[j].y * v[j].y + v[j].z * v[j].z + v[j].w * v[j].w;
;         }
; #pragma unroll
;         for (int o = 32; o >= 1; o >>= 1) ss += __shfl_xor(ss, o);
;         const float rstd = rsqrtf(ss * (1.0f / 1024.0f) + EPS);
; #pragma unroll
;         for (int j = 0; j < 4; ++j) {
;             const int col = j * 256 + lane * 4;
;             const float4 gg = *(const float4*)(g + col);
;             const float4 sh = *(const float4*)(md + col);
;             const float4 sc = *(const float4*)(md + 1024 + col);
;             const float a0 = v[j].x * rstd * gg.x * (1.0f + sc.x) + sh.x;
;             const float a1 = v[j].y * rstd * gg.y * (1.0f + sc.y) + sh.y;
;             const float a2 = v[j].z * rstd * gg.z * (1.0f + sc.z) + sh.z;
;             const float a3 = v[j].w * rstd * gg.w * (1.0f + sc.w) + sh.w;
;             u32x2 o; o.x = pk_bf16(a0, a1); o.y = pk_bf16(a2, a3);
;             *(u32x2*)(p.h + (size_t)row * D + col) = o;
;         }
	v_add_f32_e32 v8, v8, v9
	v_fmamk_f32 v8, v8, 0x3a800000, v236
	v_mul_f32_e32 v9, 0x4b800000, v8
	v_cmp_gt_f32_e32 vcc, s29, v8
	s_lshl_b32 s38, s14, 11
	s_add_u32 s36, s18, s38
	s_addc_u32 s37, s19, 0
	v_cndmask_b32_e32 v8, v8, v9, vcc
	v_rsq_f32_e32 v8, v8
	s_nop 0
	v_mul_f32_e32 v9, 0x45800000, v8
	v_cndmask_b32_e32 v10, v8, v9, vcc
	v_mul_f32_e32 v140, v108, v10
	v_mul_f32_e32 v141, v109, v10
	v_mul_f32_e32 v142, v110, v10
	v_mul_f32_e32 v143, v111, v10
	v_mul_f32_e32 v144, v112, v10
	v_mul_f32_e32 v145, v113, v10
	v_mul_f32_e32 v146, v114, v10
	v_mul_f32_e32 v147, v115, v10
	v_mul_f32_e32 v148, v116, v10
	v_mul_f32_e32 v149, v117, v10
	v_mul_f32_e32 v150, v118, v10
	v_mul_f32_e32 v151, v119, v10
	v_mul_f32_e32 v152, v120, v10
	v_mul_f32_e32 v153, v121, v10
	v_mul_f32_e32 v154, v122, v10
	v_mul_f32_e32 v155, v123, v10
	s_cmp_lt_i32 s15, s13
	s_cselect_b32 s39, s15, s14
	s_lshl_b32 s38, s39, 12
	s_add_u32 s34, s16, s38
	s_addc_u32 s35, s17, 0
	global_load_dwordx4 v[108:111], v0, s[34:35]
	global_load_dwordx4 v[112:115], v0, s[34:35] offset:1024
	global_load_dwordx4 v[116:119], v0, s[34:35] offset:2048
	global_load_dwordx4 v[120:123], v0, s[34:35] offset:3072
	s_add_i32 s15, s15, s12
	v_mul_f32_e32 v140, v60, v140
	v_mul_f32_e32 v141, v61, v141
	v_mul_f32_e32 v142, v62, v142
	v_mul_f32_e32 v143, v63, v143
	v_fma_f32 v140, v76, v140, v92
	v_fma_f32 v141, v77, v141, v93
	v_fma_f32 v142, v78, v142, v94
	v_fma_f32 v143, v79, v143, v95
	v_cvt_pk_bf16_f32 v20, v140, v141
	v_cvt_pk_bf16_f32 v21, v142, v143
	global_store_dwordx2 v2, v[20:21], s[36:37]
	v_mul_f32_e32 v144, v64, v144
	v_mul_f32_e32 v145, v65, v145
	v_mul_f32_e32 v146, v66, v146
	v_mul_f32_e32 v147, v67, v147
	v_fma_f32 v144, v80, v144, v96
	v_fma_f32 v145, v81, v145, v97
	v_fma_f32 v146, v82, v146, v98
	v_fma_f32 v147, v83, v147, v99
	v_cvt_pk_bf16_f32 v22, v144, v145
	v_cvt_pk_bf16_f32 v23, v146, v147
	global_store_dwordx2 v2, v[22:23], s[36:37] offset:512
	v_mul_f32_e32 v148, v68, v148
	v_mul_f32_e32 v149, v69, v149
	v_mul_f32_e32 v150, v70, v150
	v_mul_f32_e32 v151, v71, v151
	v_fma_f32 v148, v84, v148, v100
	v_fma_f32 v149, v85, v149, v101
	v_fma_f32 v150, v86, v150, v102
	v_fma_f32 v151, v87, v151, v103
	v_cvt_pk_bf16_f32 v24, v148, v149
	v_cvt_pk_bf16_f32 v25, v150, v151
	global_store_dwordx2 v2, v[24:25], s[36:37] offset:1024
	v_mul_f32_e32 v152, v72, v152
	v_mul_f32_e32 v153, v73, v153
	v_mul_f32_e32 v154, v74, v154
	v_mul_f32_e32 v155, v75, v155
	v_fma_f32 v152, v88, v152, v104
	v_fma_f32 v153, v89, v153, v105
	v_fma_f32 v154, v90, v154, v106
	v_fma_f32 v155, v91, v155, v107
	v_cvt_pk_bf16_f32 v26, v152, v153
	v_cvt_pk_bf16_f32 v27, v154, v155
	global_store_dwordx2 v2, v[26:27], s[36:37] offset:1536
	s_add_i32 s14, s14, s12
	s_cmp_ge_i32 s14, s13
	s_cbranch_scc1 .Lprep2_exit
	s_waitcnt vmcnt(8)
	v_mul_f32_e32 v4, v125, v125
	v_fma_f32 v4, v124, v124, v4
	v_fma_f32 v4, v126, v126, v4
	v_fma_f32 v4, v127, v127, v4
	v_mul_f32_e32 v5, v129, v129
	v_fma_f32 v5, v128, v128, v5
	v_fma_f32 v5, v130, v130, v5
	v_fma_f32 v5, v131, v131, v5
	v_mul_f32_e32 v6, v133, v133
	v_fma_f32 v6, v132, v132, v6
	v_fma_f32 v6, v134, v134, v6
	v_fma_f32 v6, v135, v135, v6
	v_mul_f32_e32 v7, v137, v137
	v_fma_f32 v7, v136, v136, v7
	v_fma_f32 v7, v138, v138, v7
	v_fma_f32 v7, v139, v139, v7
	v_add_f32_e32 v8, v4, v5
	v_add_f32_e32 v8, v8, v6
	v_add_f32_e32 v8, v8, v7
	ds_bpermute_b32 v9, v40, v8
	s_waitcnt lgkmcnt(0)
	v_add_f32_e32 v8, v8, v9
	ds_bpermute_b32 v9, v41, v8
	s_waitcnt lgkmcnt(0)
	v_add_f32_e32 v8, v8, v9
	ds_bpermute_b32 v9, v42, v8
	s_waitcnt lgkmcnt(0)
	v_add_f32_e32 v8, v8, v9
	ds_bpermute_b32 v9, v43, v8
	s_waitcnt lgkmcnt(0)
	v_add_f32_e32 v8, v8, v9
	ds_bpermute_b32 v9, v44, v8
	s_waitcnt lgkmcnt(0)
	v_add_f32_e32 v8, v8, v9
	ds_bpermute_b32 v9, v45, v8
	s_waitcnt lgkmcnt(0)
	v_add_f32_e32 v8, v8, v9
	v_fmamk_f32 v8, v8, 0x3a800000, v236
	v_mul_f32_e32 v9, 0x4b800000, v8
	v_cmp_gt_f32_e32 vcc, s29, v8
	s_lshl_b32 s38, s14, 11
	s_add_u32 s36, s18, s38
	s_addc_u32 s37, s19, 0
	v_cndmask_b32_e32 v8, v8, v9, vcc
	v_rsq_f32_e32 v8, v8
	s_nop 0
	v_mul_f32_e32 v9, 0x45800000, v8
	v_cndmask_b32_e32 v10, v8, v9, vcc
	v_mul_f32_e32 v140, v124, v10
	v_mul_f32_e32 v141, v125, v10
	v_mul_f32_e32 v142, v126, v10
	v_mul_f32_e32 v143, v127, v10
	v_mul_f32_e32 v144, v128, v10
	v_mul_f32_e32 v145, v129, v10
	v_mul_f32_e32 v146, v130, v10
	v_mul_f32_e32 v147, v131, v10
	v_mul_f32_e32 v148, v132, v10
	v_mul_f32_e32 v149, v133, v10
	v_mul_f32_e32 v150, v134, v10
	v_mul_f32_e32 v151, v135, v10
	v_mul_f32_e32 v152, v136, v10
	v_mul_f32_e32 v153, v137, v10
	v_mul_f32_e32 v154, v138, v10
	v_mul_f32_e32 v155, v139, v10
	s_cmp_lt_i32 s15, s13
	s_cselect_b32 s39, s15, s14
	s_lshl_b32 s38, s39, 12
	s_add_u32 s34, s16, s38
	s_addc_u32 s35, s17, 0
	global_load_dwordx4 v[124:127], v0, s[34:35]
	global_load_dwordx4 v[128:131], v0, s[34:35] offset:1024
	global_load_dwordx4 v[132:135], v0, s[34:35] offset:2048
	global_load_dwordx4 v[136:139], v0, s[34:35] offset:3072
	s_add_i32 s15, s15, s12
	v_mul_f32_e32 v140, v60, v140
	v_mul_f32_e32 v141, v61, v141
	v_mul_f32_e32 v142, v62, v142
	v_mul_f32_e32 v143, v63, v143
	v_fma_f32 v140, v76, v140, v92
	v_fma_f32 v141, v77, v141, v93
	v_fma_f32 v142, v78, v142, v94
	v_fma_f32 v143, v79, v143, v95
	v_cvt_pk_bf16_f32 v20, v140, v141
	v_cvt_pk_bf16_f32 v21, v142, v143
	global_store_dwordx2 v2, v[20:21], s[36:37]
	v_mul_f32_e32 v144, v64, v144
	v_mul_f32_e32 v145, v65, v145
	v_mul_f32_e32 v146, v66, v146
	v_mul_f32_e32 v147, v67, v147
	v_fma_f32 v144, v80, v144, v96
	v_fma_f32 v145, v81, v145, v97
	v_fma_f32 v146, v82, v146, v98
	v_fma_f32 v147, v83, v147, v99
	v_cvt_pk_bf16_f32 v22, v144, v145
	v_cvt_pk_bf16_f32 v23, v146, v147
	global_store_dwordx2 v2, v[22:23], s[36:37] offset:512
	v_mul_f32_e32 v148, v68, v148
	v_mul_f32_e32 v149, v69, v149
	v_mul_f32_e32 v150, v70, v150
	v_mul_f32_e32 v151, v71, v151
	v_fma_f32 v148, v84, v148, v100
	v_fma_f32 v149, v85, v149, v101
	v_fma_f32 v150, v86, v150, v102
	v_fma_f32 v151, v87, v151, v103
	v_cvt_pk_bf16_f32 v24, v148, v149
	v_cvt_pk_bf16_f32 v25, v150, v151
	global_store_dwordx2 v2, v[24:25], s[36:37] offset:1024
	v_mul_f32_e32 v152, v72, v152
	v_mul_f32_e32 v153, v73, v153
	v_mul_f32_e32 v154, v74, v154
	v_mul_f32_e32 v155, v75, v155
	v_fma_f32 v152, v88, v152, v104
	v_fma_f32 v153, v89, v153, v105
	v_fma_f32 v154, v90, v154, v106
	v_fma_f32 v155, v91, v155, v107
	v_cvt_pk_bf16_f32 v26, v152, v153
	v_cvt_pk_bf16_f32 v27, v154, v155
	global_store_dwordx2 v2, v[26:27], s[36:37] offset:1536
	s_add_i32 s14, s14, s12
	s_cmp_ge_i32 s14, s13
	s_cbranch_scc1 .Lprep2_exit
; __device__ __forceinline__ void phase_prep(const Params& p, int l, int mode) {
;     ...
;         for (int j = 0; j < 4; ++j) {
;             v[j] = *(const float4*)(xr + j * 256 + lane * 4);
;             ss += v[j].x * v[j].x + v[j].y * v[j].y + v[j].z * v[j].z + v[j].w * v[j].w;
;         }
; #pragma unroll
;         for (int o = 32; o >= 1; o >>= 1) ss += __shfl_xor(ss, o);
;         const float rstd = rsqrtf(ss * (1.0f / 1024.0f) + EPS);
; #pragma unroll
;         for (int j = 0; j < 4; ++j) {
;             const int col = j * 256 + lane * 4;
;             const float4 gg = *(const float4*)(g + col);
;             const float4 sh = *(const float4*)(md + col);
;             const float4 sc = *(const float4*)(md + 1024 + col);
;             const float a0 = v[j].x * rstd * gg.x * (1.0f + sc.x) + sh.x;
;             const float a1 = v[j].y * rstd * gg.y * (1.0f + sc.y) + sh.y;
;             const float a2 = v[j].z * rstd * gg.z * (1.0f + sc.z) + sh.z;
;             const float a3 = v[j].w * rstd * gg.w * (1.0f + sc.w) + sh.w;
;             u32x2 o; o.x = pk_bf16(a0, a1); o.y = pk_bf16(a2, a3);
;             *(u32x2*)(p.h + (size_t)row * D + col) = o;
;         }
.Lprep2_loop:
	s_waitcnt vmcnt(12)
	v_mul_f32_e32 v4, v109, v109
	v_fma_f32 v4, v108, v108, v4
	v_fma_f32 v4, v110, v110, v4
	v_fma_f32 v4, v111, v111, v4
	v_mul_f32_e32 v5, v113, v113
	v_fma_f32 v5, v112, v112, v5
	v_fma_f32 v5, v114, v114, v5
	v_fma_f32 v5, v115, v115, v5
	v_mul_f32_e32 v6, v117, v117
	v_fma_f32 v6, v116, v116, v6
	v_fma_f32 v6, v118, v118, v6
	v_fma_f32 v6, v119, v119, v6
	v_mul_f32_e32 v7, v121, v121
	v_fma_f32 v7, v120, v120, v7
	v_fma_f32 v7, v122, v122, v7
	v_fma_f32 v7, v123, v123, v7
	v_add_f32_e32 v8, v4, v5
	v_add_f32_e32 v8, v8, v6
	v_add_f32_e32 v8, v8, v7
	ds_bpermute_b32 v9, v40, v8
	s_waitcnt lgkmcnt(0)
	v_add_f32_e32 v8, v8, v9
	ds_bpermute_b32 v9, v41, v8
	s_waitcnt lgkmcnt(0)
	v_add_f32_e32 v8, v8, v9
	ds_bpermute_b32 v9, v42, v8
	s_waitcnt lgkmcnt(0)
	v_add_f32_e32 v8, v8, v9
	ds_bpermute_b32 v9, v43, v8
	s_waitcnt lgkmcnt(0)
	v_add_f32_e32 v8, v8, v9
	ds_bpermute_b32 v9, v44, v8
	s_waitcnt lgkmcnt(0)
	v_add_f32_e32 v8, v8, v9
	ds_bpermute_b32 v9, v45, v8
	s_waitcnt lgkmcnt(0)
	v_add_f32_e32 v8, v8, v9
	v_fmamk_f32 v8, v8, 0x3a800000, v236
	v_mul_f32_e32 v9, 0x4b800000, v8
	v_cmp_gt_f32_e32 vcc, s29, v8
	s_lshl_b32 s38, s14, 11
	s_add_u32 s36, s18, s38
	s_addc_u32 s37, s19, 0
	v_cndmask_b32_e32 v8, v8, v9, vcc
	v_rsq_f32_e32 v8, v8
	s_nop 0
	v_mul_f32_e32 v9, 0x45800000, v8
	v_cndmask_b32_e32 v10, v8, v9, vcc
	v_mul_f32_e32 v140, v108, v10
	v_mul_f32_e32 v141, v109, v10
	v_mul_f32_e32 v142, v110, v10
	v_mul_f32_e32 v143, v111, v10
	v_mul_f32_e32 v144, v112, v10
	v_mul_f32_e32 v145, v113, v10
	v_mul_f32_e32 v146, v114, v10
	v_mul_f32_e32 v147, v115, v10
	v_mul_f32_e32 v148, v116, v10
	v_mul_f32_e32 v149, v117, v10
	v_mul_f32_e32 v150, v118, v10
	v_mul_f32_e32 v151, v119, v10
	v_mul_f32_e32 v152, v120, v10
	v_mul_f32_e32 v153, v121, v10
	v_mul_f32_e32 v154, v122, v10
	v_mul_f32_e32 v155, v123, v10
	s_cmp_lt_i32 s15, s13
	s_cselect_b32 s39, s15, s14
	s_lshl_b32 s38, s39, 12
	s_add_u32 s34, s16, s38
	s_addc_u32 s35, s17, 0
	global_load_dwordx4 v[108:111], v0, s[34:35]
	global_load_dwordx4 v[112:115], v0, s[34:35] offset:1024
	global_load_dwordx4 v[116:119], v0, s[34:35] offset:2048
	global_load_dwordx4 v[120:123], v0, s[34:35] offset:3072
	s_add_i32 s15, s15, s12
	v_mul_f32_e32 v140, v60, v140
	v_mul_f32_e32 v141, v61, v141
	v_mul_f32_e32 v142, v62, v142
	v_mul_f32_e32 v143, v63, v143
	v_fma_f32 v140, v76, v140, v92
	v_fma_f32 v141, v77, v141, v93
	v_fma_f32 v142, v78, v142, v94
	v_fma_f32 v143, v79, v143, v95
	v_cvt_pk_bf16_f32 v20, v140, v141
	v_cvt_pk_bf16_f32 v21, v142, v143
	global_store_dwordx2 v2, v[20:21], s[36:37]
	v_mul_f32_e32 v144, v64, v144
	v_mul_f32_e32 v145, v65, v145
	v_mul_f32_e32 v146, v66, v146
	v_mul_f32_e32 v147, v67, v147
	v_fma_f32 v144, v80, v144, v96
	v_fma_f32 v145, v81, v145, v97
	v_fma_f32 v146, v82, v146, v98
	v_fma_f32 v147, v83, v147, v99
	v_cvt_pk_bf16_f32 v22, v144, v145
	v_cvt_pk_bf16_f32 v23, v146, v147
	global_store_dwordx2 v2, v[22:23], s[36:37] offset:512
	v_mul_f32_e32 v148, v68, v148
	v_mul_f32_e32 v149, v69, v149
	v_mul_f32_e32 v150, v70, v150
	v_mul_f32_e32 v151, v71, v151
	v_fma_f32 v148, v84, v148, v100
	v_fma_f32 v149, v85, v149, v101
	v_fma_f32 v150, v86, v150, v102
	v_fma_f32 v151, v87, v151, v103
	v_cvt_pk_bf16_f32 v24, v148, v149
	v_cvt_pk_bf16_f32 v25, v150, v151
	global_store_dwordx2 v2, v[24:25], s[36:37] offset:1024
	v_mul_f32_e32 v152, v72, v152
	v_mul_f32_e32 v153, v73, v153
	v_mul_f32_e32 v154, v74, v154
	v_mul_f32_e32 v155, v75, v155
	v_fma_f32 v152, v88, v152, v104
	v_fma_f32 v153, v89, v153, v105
	v_fma_f32 v154, v90, v154, v106
	v_fma_f32 v155, v91, v155, v107
	v_cvt_pk_bf16_f32 v26, v152, v153
	v_cvt_pk_bf16_f32 v27, v154, v155
	global_store_dwordx2 v2, v[26:27], s[36:37] offset:1536
	s_add_i32 s14, s14, s12
	s_cmp_ge_i32 s14, s13
	s_cbranch_scc1 .Lprep2_exit
; __device__ __forceinline__ void phase_prep(const Params& p, int l, int mode) {
;     ...
;     for (int lrow = lr_lo + xj_ * 8 + w; lrow < lr_hi; lrow += xn_ * 8) {
;         const int row = lrow < SEQ ? xb_ * SEQ + lrow : MLAT + xb_ * CTXL + (lrow - SEQ);
;         const float* xr = xin_row(p, l, row);
;         const int bv = row < MLAT ? (row >> 12) : 8;
;         const float* md = p.mod + ((size_t)l * 9 + bv) * 3072;
;         float4 v[4]; float ss = 0.f;
; #pragma unroll
;         for (int j = 0; j < 4; ++j) {
;             v[j] = *(const float4*)(xr + j * 256 + lane * 4);
;             ss += v[j].x * v[j].x + v[j].y * v[j].y + v[j].z * v[j].z + v[j].w * v[j].w;
;         }
; #pragma unroll
;         for (int o = 32; o >= 1; o >>= 1) ss += __shfl_xor(ss, o);
;         const float rstd = rsqrtf(ss * (1.0f / 1024.0f) + EPS);
; #pragma unroll
;         for (int j = 0; j < 4; ++j) {
;             const int col = j * 256 + lane * 4;
;             const float4 gg = *(const float4*)(g + col);
;             const float4 sh = *(const float4*)(md + col);
;             const float4 sc = *(const float4*)(md + 1024 + col);
;             const float a0 = v[j].x * rstd * gg.x * (1.0f + sc.x) + sh.x;
;             const float a1 = v[j].y * rstd * gg.y * (1.0f + sc.y) + sh.y;
;             const float a2 = v[j].z * rstd * gg.z * (1.0f + sc.z) + sh.z;
;             const float a3 = v[j].w * rstd * gg.w * (1.0f + sc.w) + sh.w;
;             u32x2 o; o.x = pk_bf16(a0, a1); o.y = pk_bf16(a2, a3);
;             *(u32x2*)(p.h + (size_t)row * D + col) = o;
;         }
	s_waitcnt vmcnt(12)
	v_mul_f32_e32 v4, v125, v125
	v_fma_f32 v4, v124, v124, v4
	v_fma_f32 v4, v126, v126, v4
	v_fma_f32 v4, v127, v127, v4
	v_mul_f32_e32 v5, v129, v129
	v_fma_f32 v5, v128, v128, v5
	v_fma_f32 v5, v130, v130, v5
	v_fma_f32 v5, v131, v131, v5
	v_mul_f32_e32 v6, v133, v133
	v_fma_f32 v6, v132, v132, v6
	v_fma_f32 v6, v134, v134, v6
	v_fma_f32 v6, v135, v135, v6
	v_mul_f32_e32 v7, v137, v137
	v_fma_f32 v7, v136, v136, v7
	v_fma_f32 v7, v138, v138, v7
	v_fma_f32 v7, v139, v139, v7
	v_add_f32_e32 v8, v4, v5
	v_add_f32_e32 v8, v8, v6
	v_add_f32_e32 v8, v8, v7
	ds_bpermute_b32 v9, v40, v8
	s_waitcnt lgkmcnt(0)
	v_add_f32_e32 v8, v8, v9
	ds_bpermute_b32 v9, v41, v8
	s_waitcnt lgkmcnt(0)
	v_add_f32_e32 v8, v8, v9
	ds_bpermute_b32 v9, v42, v8
	s_waitcnt lgkmcnt(0)
	v_add_f32_e32 v8, v8, v9
	ds_bpermute_b32 v9, v43, v8
	s_waitcnt lgkmcnt(0)
	v_add_f32_e32 v8, v8, v9
	ds_bpermute_b32 v9, v44, v8
	s_waitcnt lgkmcnt(0)
	v_add_f32_e32 v8, v8, v9
	ds_bpermute_b32 v9, v45, v8
	s_waitcnt lgkmcnt(0)
	v_add_f32_e32 v8, v8, v9
	v_fmamk_f32 v8, v8, 0x3a800000, v236
	v_mul_f32_e32 v9, 0x4b800000, v8
	v_cmp_gt_f32_e32 vcc, s29, v8
	s_lshl_b32 s38, s14, 11
	s_add_u32 s36, s18, s38
	s_addc_u32 s37, s19, 0
	v_cndmask_b32_e32 v8, v8, v9, vcc
	v_rsq_f32_e32 v8, v8
	s_nop 0
	v_mul_f32_e32 v9, 0x45800000, v8
	v_cndmask_b32_e32 v10, v8, v9, vcc
	v_mul_f32_e32 v140, v124, v10
	v_mul_f32_e32 v141, v125, v10
	v_mul_f32_e32 v142, v126, v10
	v_mul_f32_e32 v143, v127, v10
	v_mul_f32_e32 v144, v128, v10
	v_mul_f32_e32 v145, v129, v10
	v_mul_f32_e32 v146, v130, v10
	v_mul_f32_e32 v147, v131, v10
	v_mul_f32_e32 v148, v132, v10
	v_mul_f32_e32 v149, v133, v10
	v_mul_f32_e32 v150, v134, v10
	v_mul_f32_e32 v151, v135, v10
	v_mul_f32_e32 v152, v136, v10
	v_mul_f32_e32 v153, v137, v10
	v_mul_f32_e32 v154, v138, v10
	v_mul_f32_e32 v155, v139, v10
	s_cmp_lt_i32 s15, s13
	s_cselect_b32 s39, s15, s14
	s_lshl_b32 s38, s39, 12
	s_add_u32 s34, s16, s38
	s_addc_u32 s35, s17, 0
	global_load_dwordx4 v[124:127], v0, s[34:35]
	global_load_dwordx4 v[128:131], v0, s[34:35] offset:1024
	global_load_dwordx4 v[132:135], v0, s[34:35] offset:2048
	global_load_dwordx4 v[136:139], v0, s[34:35] offset:3072
	s_add_i32 s15, s15, s12
	v_mul_f32_e32 v140, v60, v140
	v_mul_f32_e32 v141, v61, v141
	v_mul_f32_e32 v142, v62, v142
	v_mul_f32_e32 v143, v63, v143
	v_fma_f32 v140, v76, v140, v92
	v_fma_f32 v141, v77, v141, v93
	v_fma_f32 v142, v78, v142, v94
	v_fma_f32 v143, v79, v143, v95
	v_cvt_pk_bf16_f32 v20, v140, v141
	v_cvt_pk_bf16_f32 v21, v142, v143
	global_store_dwordx2 v2, v[20:21], s[36:37]
	v_mul_f32_e32 v144, v64, v144
	v_mul_f32_e32 v145, v65, v145
	v_mul_f32_e32 v146, v66, v146
	v_mul_f32_e32 v147, v67, v147
	v_fma_f32 v144, v80, v144, v96
	v_fma_f32 v145, v81, v145, v97
	v_fma_f32 v146, v82, v146, v98
	v_fma_f32 v147, v83, v147, v99
	v_cvt_pk_bf16_f32 v22, v144, v145
	v_cvt_pk_bf16_f32 v23, v146, v147
	global_store_dwordx2 v2, v[22:23], s[36:37] offset:512
	v_mul_f32_e32 v148, v68, v148
	v_mul_f32_e32 v149, v69, v149
	v_mul_f32_e32 v150, v70, v150
	v_mul_f32_e32 v151, v71, v151
	v_fma_f32 v148, v84, v148, v100
	v_fma_f32 v149, v85, v149, v101
	v_fma_f32 v150, v86, v150, v102
	v_fma_f32 v151, v87, v151, v103
	v_cvt_pk_bf16_f32 v24, v148, v149
	v_cvt_pk_bf16_f32 v25, v150, v151
	global_store_dwordx2 v2, v[24:25], s[36:37] offset:1024
	v_mul_f32_e32 v152, v72, v152
	v_mul_f32_e32 v153, v73, v153
	v_mul_f32_e32 v154, v74, v154
	v_mul_f32_e32 v155, v75, v155
	v_fma_f32 v152, v88, v152, v104
	v_fma_f32 v153, v89, v153, v105
	v_fma_f32 v154, v90, v154, v106
	v_fma_f32 v155, v91, v155, v107
	v_cvt_pk_bf16_f32 v26, v152, v153
	v_cvt_pk_bf16_f32 v27, v154, v155
	global_store_dwordx2 v2, v[26:27], s[36:37] offset:1536
	s_add_i32 s14, s14, s12
	s_cmp_ge_i32 s14, s13
	s_cbranch_scc1 .Lprep2_exit
	s_branch .Lprep2_loop
.Lprep2_exit:
	s_waitcnt vmcnt(0)
.LBB0_787:
	s_mov_b64 s[4:5], 0
.LBB0_788:
	s_and_b64 vcc, exec, s[4:5]
	s_cbranch_vccz .LBB0_798
	v_readlane_b32 s12, v253, 0
	v_readlane_b32 s14, v253, 2
	v_readlane_b32 s15, v253, 3
	s_cmp_lt_i32 s68, 1
	s_mov_b64 s[4:5], s[14:15]
	v_readlane_b32 s13, v253, 1
	v_readlane_b32 s16, v253, 4
	v_readlane_b32 s17, v253, 5
	v_readlane_b32 s18, v253, 6
	v_readlane_b32 s19, v253, 7
	v_readlane_b32 s20, v253, 8
	v_readlane_b32 s21, v253, 9
	v_readlane_b32 s22, v253, 10
	v_readlane_b32 s23, v253, 11
	v_readlane_b32 s24, v253, 12
	v_readlane_b32 s25, v253, 13
	v_readlane_b32 s26, v253, 14
	v_readlane_b32 s27, v253, 15
	s_cbranch_scc1 .LBB0_793
	v_readlane_b32 s12, v253, 0
	v_readlane_b32 s16, v253, 4
	v_readlane_b32 s17, v253, 5
	s_cmp_lt_i32 s68, 2
	s_mov_b64 s[4:5], s[16:17]
	v_readlane_b32 s13, v253, 1
	v_readlane_b32 s14, v253, 2
	v_readlane_b32 s15, v253, 3
	v_readlane_b32 s18, v253, 6
	v_readlane_b32 s19, v253, 7
	v_readlane_b32 s20, v253, 8
	v_readlane_b32 s21, v253, 9
	v_readlane_b32 s22, v253, 10
	v_readlane_b32 s23, v253, 11
	v_readlane_b32 s24, v253, 12
	v_readlane_b32 s25, v253, 13
	v_readlane_b32 s26, v253, 14
	v_readlane_b32 s27, v253, 15
	s_cbranch_scc1 .LBB0_793
	v_readlane_b32 s12, v253, 0
	v_readlane_b32 s18, v253, 6
	v_readlane_b32 s19, v253, 7
	s_cmp_lg_u32 s68, 2
	s_mov_b64 s[4:5], s[18:19]
	v_readlane_b32 s13, v253, 1
	v_readlane_b32 s14, v253, 2
	v_readlane_b32 s15, v253, 3
	v_readlane_b32 s16, v253, 4
	v_readlane_b32 s17, v253, 5
	v_readlane_b32 s20, v253, 8
	v_readlane_b32 s21, v253, 9
	v_readlane_b32 s22, v253, 10
	v_readlane_b32 s23, v253, 11
	v_readlane_b32 s24, v253, 12
	v_readlane_b32 s25, v253, 13
	v_readlane_b32 s26, v253, 14
	v_readlane_b32 s27, v253, 15
	s_cbranch_scc0 .LBB0_793
	v_readlane_b32 s12, v253, 0
	v_readlane_b32 s20, v253, 8
	v_readlane_b32 s21, v253, 9
	s_mov_b64 s[4:5], s[20:21]
	v_readlane_b32 s13, v253, 1
	v_readlane_b32 s14, v253, 2
	v_readlane_b32 s15, v253, 3
	v_readlane_b32 s16, v253, 4
	v_readlane_b32 s17, v253, 5
	v_readlane_b32 s18, v253, 6
	v_readlane_b32 s19, v253, 7
	v_readlane_b32 s22, v253, 10
	v_readlane_b32 s23, v253, 11
	v_readlane_b32 s24, v253, 12
	v_readlane_b32 s25, v253, 13
	v_readlane_b32 s26, v253, 14
	v_readlane_b32 s27, v253, 15
